# prologue: the 64 workgroups without a modulation-GEMV task convert all of layer-0 w_in while the other 192 run the GEMV
# baseline (speedup 1.0000x reference)
.LBB0_30:
	s_lshl_b32 s0, s10, 3
	s_add_i32 s12, s0, s11
	v_readlane_b32 s0, v253, 5
	s_lshl_b32 s88, s0, 3
	s_mul_i32 s0, s11, 0x2200
	s_add_i32 s13, s0, 0
	v_readlane_b32 s1, v253, 6
	s_add_u32 s0, s54, 0x200000
	s_addc_u32 s1, s55, 0
	v_writelane_b32 v253, s0, 44
	s_cmpk_lt_i32 s12, 0x1000
	v_lshrrev_b32_e32 v14, 5, v39
	v_writelane_b32 v253, s1, 45
	s_cselect_b64 s[0:1], -1, 0
	s_cmpk_gt_i32 s12, 0xfff
	v_lshlrev_b32_e32 v16, 2, v38
	v_lshrrev_b32_e32 v15, 3, v39
	s_cbranch_scc1 .LBB0_33
	v_and_b32_e32 v2, 0x7c, v16
	v_mov_b32_e32 v3, 0
	v_lshl_add_u64 v[0:1], s[56:57], 0, v[2:3]
	v_add_u32_e32 v5, s13, v2
	v_and_b32_e32 v2, 56, v36
	v_readlane_b32 s2, v253, 44
	v_mul_u32_u24_e32 v4, 0x84, v2
	v_lshlrev_b32_e32 v2, 1, v2
	v_readlane_b32 s3, v253, 45
	v_mul_u32_u24_e32 v6, 0x84, v14
	v_lshlrev_b32_e32 v7, 2, v15
	v_lshl_add_u64 v[2:3], s[2:3], 0, v[2:3]
	s_lshl_b32 s2, s10, 8
	s_lshl_b32 s3, s11, 5
	s_add_i32 s6, s2, s3
	v_readlane_b32 s2, v253, 5
	v_add_u32_e32 v5, v5, v6
	v_add3_u32 v4, s13, v4, v7
	s_lshl_b32 s7, s2, 8
	v_add_u32_e32 v6, 0x400, v5
	v_add_u32_e32 v7, 0x800, v5
	v_add_u32_e32 v8, 0xc00, v5
	v_add_u32_e32 v9, 0x1000, v5
	v_add_u32_e32 v10, 0x1400, v5
	v_add_u32_e32 v11, 0x1800, v5
	v_add_u32_e32 v12, 0x1c00, v5
	s_mov_b32 s8, s12
	v_readlane_b32 s3, v253, 6
	v_readlane_b32 s100, v253, 5
	s_mov_b32 s101, s88
	s_cmpk_lg_i32 s100, 0x100
	s_cbranch_scc1 .Lcvt0_go
	s_cmpk_lt_i32 s10, 0xc0
	s_cbranch_scc1 .LBB0_33
	s_sub_i32 s8, s10, 0xc0
	s_lshl_b32 s8, s8, 3
	s_add_i32 s8, s8, s11
	s_lshl_b32 s6, s8, 5
	s_movk_i32 s7, 0x4000
	s_movk_i32 s101, 0x200
.Lcvt0_go:
.LBB0_32:
	s_ashr_i32 s2, s8, 31
	s_lshr_b32 s2, s2, 25
	s_add_i32 s2, s8, s2
	s_ashr_i32 s3, s2, 7
	s_lshl_b32 s2, s3, 6
	s_lshl_b32 s3, s3, 12
	v_or_b32_e32 v18, s2, v14
	s_sub_i32 s4, s6, s3
	v_or_b32_e32 v28, 10, v18
	v_or_b32_e32 v30, 12, v18
	v_or_b32_e32 v32, 14, v18
	v_or_b32_e32 v44, 24, v18
	v_or_b32_e32 v46, 26, v18
	v_or_b32_e32 v48, 28, v18
	v_or_b32_e32 v50, 30, v18
	v_or_b32_e32 v52, 32, v18
	v_or_b32_e32 v54, 34, v18
	v_or_b32_e32 v56, 36, v18
	v_or_b32_e32 v58, 38, v18
	v_or_b32_e32 v60, 40, v18
	v_or_b32_e32 v62, 42, v18
	s_ashr_i32 s5, s4, 31
	v_ashrrev_i32_e32 v19, 31, v18
	v_or_b32_e32 v20, 2, v18
	v_or_b32_e32 v22, 4, v18
	v_or_b32_e32 v24, 6, v18
	v_or_b32_e32 v26, 8, v18
	v_or_b32_e32 v34, 16, v18
	v_or_b32_e32 v38, 18, v18
	v_or_b32_e32 v40, 20, v18
	v_or_b32_e32 v42, 22, v18
	v_or_b32_e32 v64, 44, v18
	v_or_b32_e32 v66, 46, v18
	v_or_b32_e32 v68, 48, v18
	v_or_b32_e32 v70, 50, v18
	v_or_b32_e32 v72, 52, v18
	v_or_b32_e32 v74, 54, v18
	v_or_b32_e32 v76, 56, v18
	v_or_b32_e32 v78, 58, v18
	v_or_b32_e32 v80, 60, v18
	v_or_b32_e32 v82, 62, v18
	v_ashrrev_i32_e32 v29, 31, v28
	v_ashrrev_i32_e32 v31, 31, v30
	v_ashrrev_i32_e32 v33, 31, v32
	v_ashrrev_i32_e32 v45, 31, v44
	v_ashrrev_i32_e32 v47, 31, v46
	v_ashrrev_i32_e32 v49, 31, v48
	v_ashrrev_i32_e32 v51, 31, v50
	v_ashrrev_i32_e32 v53, 31, v52
	v_ashrrev_i32_e32 v55, 31, v54
	v_ashrrev_i32_e32 v57, 31, v56
	v_ashrrev_i32_e32 v59, 31, v58
	v_ashrrev_i32_e32 v61, 31, v60
	v_ashrrev_i32_e32 v63, 31, v62
	v_lshlrev_b64 v[18:19], 14, v[18:19]
	v_ashrrev_i32_e32 v21, 31, v20
	v_ashrrev_i32_e32 v23, 31, v22
	v_ashrrev_i32_e32 v25, 31, v24
	v_ashrrev_i32_e32 v27, 31, v26
	v_ashrrev_i32_e32 v35, 31, v34
	v_ashrrev_i32_e32 v39, 31, v38
	v_ashrrev_i32_e32 v41, 31, v40
	v_ashrrev_i32_e32 v43, 31, v42
	v_ashrrev_i32_e32 v65, 31, v64
	v_ashrrev_i32_e32 v67, 31, v66
	v_ashrrev_i32_e32 v69, 31, v68
	v_ashrrev_i32_e32 v71, 31, v70
	v_ashrrev_i32_e32 v73, 31, v72
	v_ashrrev_i32_e32 v75, 31, v74
	v_ashrrev_i32_e32 v77, 31, v76
	v_ashrrev_i32_e32 v79, 31, v78
	v_ashrrev_i32_e32 v81, 31, v80
	v_ashrrev_i32_e32 v83, 31, v82
	v_lshl_add_u64 v[84:85], s[4:5], 2, v[0:1]
	v_lshlrev_b64 v[28:29], 14, v[28:29]
	v_lshlrev_b64 v[30:31], 14, v[30:31]
	v_lshlrev_b64 v[32:33], 14, v[32:33]
	v_lshlrev_b64 v[44:45], 14, v[44:45]
	v_lshlrev_b64 v[46:47], 14, v[46:47]
	v_lshlrev_b64 v[48:49], 14, v[48:49]
	v_lshlrev_b64 v[50:51], 14, v[50:51]
	v_lshlrev_b64 v[52:53], 14, v[52:53]
	v_lshlrev_b64 v[54:55], 14, v[54:55]
	v_lshlrev_b64 v[56:57], 14, v[56:57]
	v_lshlrev_b64 v[58:59], 14, v[58:59]
	v_lshlrev_b64 v[60:61], 14, v[60:61]
	v_lshlrev_b64 v[62:63], 14, v[62:63]
	v_lshl_add_u64 v[18:19], v[84:85], 0, v[18:19]
	v_lshlrev_b64 v[20:21], 14, v[20:21]
	v_lshlrev_b64 v[22:23], 14, v[22:23]
	v_lshlrev_b64 v[24:25], 14, v[24:25]
	v_lshlrev_b64 v[26:27], 14, v[26:27]
	v_lshlrev_b64 v[34:35], 14, v[34:35]
	v_lshlrev_b64 v[38:39], 14, v[38:39]
	v_lshlrev_b64 v[40:41], 14, v[40:41]
	v_lshlrev_b64 v[42:43], 14, v[42:43]
	v_lshlrev_b64 v[64:65], 14, v[64:65]
	v_lshlrev_b64 v[66:67], 14, v[66:67]
	v_lshlrev_b64 v[68:69], 14, v[68:69]
	v_lshlrev_b64 v[70:71], 14, v[70:71]
	v_lshlrev_b64 v[72:73], 14, v[72:73]
	v_lshlrev_b64 v[74:75], 14, v[74:75]
	v_lshlrev_b64 v[76:77], 14, v[76:77]
	v_lshlrev_b64 v[78:79], 14, v[78:79]
	v_lshlrev_b64 v[80:81], 14, v[80:81]
	v_lshlrev_b64 v[82:83], 14, v[82:83]
	v_lshl_add_u64 v[28:29], v[84:85], 0, v[28:29]
	v_lshl_add_u64 v[30:31], v[84:85], 0, v[30:31]
	v_lshl_add_u64 v[32:33], v[84:85], 0, v[32:33]
	v_lshl_add_u64 v[44:45], v[84:85], 0, v[44:45]
	v_lshl_add_u64 v[46:47], v[84:85], 0, v[46:47]
	v_lshl_add_u64 v[48:49], v[84:85], 0, v[48:49]
	v_lshl_add_u64 v[50:51], v[84:85], 0, v[50:51]
	v_lshl_add_u64 v[52:53], v[84:85], 0, v[52:53]
	v_lshl_add_u64 v[54:55], v[84:85], 0, v[54:55]
	v_lshl_add_u64 v[56:57], v[84:85], 0, v[56:57]
	v_lshl_add_u64 v[58:59], v[84:85], 0, v[58:59]
	v_lshl_add_u64 v[60:61], v[84:85], 0, v[60:61]
	v_lshl_add_u64 v[62:63], v[84:85], 0, v[62:63]
	v_lshl_add_u64 v[20:21], v[84:85], 0, v[20:21]
	v_lshl_add_u64 v[22:23], v[84:85], 0, v[22:23]
	v_lshl_add_u64 v[24:25], v[84:85], 0, v[24:25]
	v_lshl_add_u64 v[26:27], v[84:85], 0, v[26:27]
	v_lshl_add_u64 v[34:35], v[84:85], 0, v[34:35]
	v_lshl_add_u64 v[38:39], v[84:85], 0, v[38:39]
	v_lshl_add_u64 v[40:41], v[84:85], 0, v[40:41]
	v_lshl_add_u64 v[42:43], v[84:85], 0, v[42:43]
	v_lshl_add_u64 v[64:65], v[84:85], 0, v[64:65]
	v_lshl_add_u64 v[66:67], v[84:85], 0, v[66:67]
	v_lshl_add_u64 v[68:69], v[84:85], 0, v[68:69]
	v_lshl_add_u64 v[70:71], v[84:85], 0, v[70:71]
	v_lshl_add_u64 v[72:73], v[84:85], 0, v[72:73]
	v_lshl_add_u64 v[74:75], v[84:85], 0, v[74:75]
	v_lshl_add_u64 v[76:77], v[84:85], 0, v[76:77]
	v_lshl_add_u64 v[78:79], v[84:85], 0, v[78:79]
	v_lshl_add_u64 v[80:81], v[84:85], 0, v[80:81]
	v_lshl_add_u64 v[82:83], v[84:85], 0, v[82:83]
	global_load_dword v13, v[18:19], off nt
	global_load_dword v17, v[20:21], off nt
	global_load_dword v37, v[22:23], off nt
	global_load_dword v84, v[24:25], off nt
	global_load_dword v85, v[26:27], off nt
	s_nop 0
	global_load_dword v28, v[28:29], off nt
	s_nop 0
	global_load_dword v29, v[30:31], off nt
	s_nop 0
	global_load_dword v30, v[32:33], off nt
	global_load_dword v31, v[34:35], off nt
	s_nop 0
	global_load_dword v32, v[38:39], off nt
	global_load_dword v33, v[40:41], off nt
	global_load_dword v86, v[42:43], off nt
	s_nop 0
	global_load_dword v44, v[44:45], off nt
	s_nop 0
	global_load_dword v45, v[46:47], off nt
	s_nop 0
	global_load_dword v46, v[48:49], off nt
	global_load_dword v47, v[50:51], off nt
	s_nop 0
	global_load_dword v48, v[52:53], off nt
	global_load_dword v49, v[54:55], off nt
	global_load_dword v50, v[56:57], off nt
	global_load_dword v51, v[58:59], off nt
	s_nop 0
	global_load_dword v52, v[60:61], off nt
	global_load_dword v53, v[62:63], off nt
	global_load_dword v54, v[64:65], off nt
	global_load_dword v55, v[66:67], off nt
	global_load_dword v56, v[68:69], off nt
	global_load_dword v57, v[70:71], off nt
	global_load_dword v58, v[72:73], off nt
	global_load_dword v59, v[74:75], off nt
	global_load_dword v60, v[76:77], off nt
	global_load_dword v61, v[78:79], off nt
	global_load_dword v62, v[80:81], off nt
	global_load_dword v63, v[82:83], off nt
	v_add_u32_e32 v20, s4, v15
	s_ashr_i32 s3, s2, 31
	v_ashrrev_i32_e32 v21, 31, v20
	v_add_u32_e32 v22, 8, v20
	v_add_u32_e32 v24, 16, v20
	v_add_u32_e32 v26, 24, v20
	v_lshl_add_u64 v[18:19], s[2:3], 1, v[2:3]
	v_lshlrev_b64 v[20:21], 12, v[20:21]
	v_ashrrev_i32_e32 v23, 31, v22
	v_ashrrev_i32_e32 v25, 31, v24
	v_ashrrev_i32_e32 v27, 31, v26
	s_waitcnt vmcnt(30)
	ds_write2_b32 v5, v13, v17 offset1:66
	s_waitcnt vmcnt(28)
	ds_write2_b32 v5, v37, v84 offset0:132 offset1:198
	s_waitcnt vmcnt(26)
	ds_write2_b32 v6, v85, v28 offset0:8 offset1:74
	s_waitcnt vmcnt(24)
	ds_write2_b32 v6, v29, v30 offset0:140 offset1:206
	s_waitcnt vmcnt(22)
	ds_write2_b32 v7, v31, v32 offset0:16 offset1:82
	s_waitcnt vmcnt(20)
	ds_write2_b32 v7, v33, v86 offset0:148 offset1:214
	s_waitcnt vmcnt(18)
	ds_write2_b32 v8, v44, v45 offset0:24 offset1:90
	s_waitcnt vmcnt(16)
	ds_write2_b32 v8, v46, v47 offset0:156 offset1:222
	s_waitcnt vmcnt(14)
	ds_write2_b32 v9, v48, v49 offset0:32 offset1:98
	s_waitcnt vmcnt(12)
	ds_write2_b32 v9, v50, v51 offset0:164 offset1:230
	s_waitcnt vmcnt(10)
	ds_write2_b32 v10, v52, v53 offset0:40 offset1:106
	s_waitcnt vmcnt(8)
	ds_write2_b32 v10, v54, v55 offset0:172 offset1:238
	s_waitcnt vmcnt(6)
	ds_write2_b32 v11, v56, v57 offset0:48 offset1:114
	s_waitcnt vmcnt(4)
	ds_write2_b32 v11, v58, v59 offset0:180 offset1:246
	s_waitcnt vmcnt(2)
	ds_write2_b32 v12, v60, v61 offset0:56 offset1:122
	s_waitcnt vmcnt(0)
	ds_write2_b32 v12, v62, v63 offset0:188 offset1:254
	v_lshl_add_u64 v[34:35], v[18:19], 0, v[20:21]
	v_lshlrev_b64 v[20:21], 12, v[22:23]
	v_lshlrev_b64 v[22:23], 12, v[24:25]
	v_lshlrev_b64 v[24:25], 12, v[26:27]
	s_waitcnt lgkmcnt(0)
	v_lshl_add_u64 v[40:41], v[18:19], 0, v[22:23]
	v_lshl_add_u64 v[42:43], v[18:19], 0, v[24:25]
	ds_read2_b32 v[22:23], v4 offset0:33 offset1:41
	ds_read2_b32 v[24:25], v4 offset1:8
	ds_read2_b32 v[26:27], v4 offset0:66 offset1:74
	ds_read2_b32 v[28:29], v4 offset0:99 offset1:107
	ds_read2_b32 v[30:31], v4 offset0:132 offset1:140
	ds_read2_b32 v[32:33], v4 offset0:165 offset1:173
	ds_read2_b32 v[44:45], v4 offset0:198 offset1:206
	ds_read2_b32 v[46:47], v4 offset0:231 offset1:239
	ds_read2_b32 v[48:49], v4 offset0:49 offset1:57
	ds_read2_b32 v[50:51], v4 offset0:16 offset1:24
	ds_read2_b32 v[52:53], v4 offset0:82 offset1:90
	ds_read2_b32 v[54:55], v4 offset0:115 offset1:123
	ds_read2_b32 v[56:57], v4 offset0:148 offset1:156
	ds_read2_b32 v[58:59], v4 offset0:181 offset1:189
	ds_read2_b32 v[60:61], v4 offset0:214 offset1:222
	ds_read2_b32 v[62:63], v4 offset0:247 offset1:255
	v_lshl_add_u64 v[38:39], v[18:19], 0, v[20:21]
	s_waitcnt lgkmcnt(14)
	v_cvt_pk_bf16_f32 v18, v24, v22
	s_waitcnt lgkmcnt(12)
	v_cvt_pk_bf16_f32 v19, v26, v28
	s_waitcnt lgkmcnt(10)
	v_cvt_pk_bf16_f32 v20, v30, v32
	s_waitcnt lgkmcnt(8)
	v_cvt_pk_bf16_f32 v21, v44, v46
	v_cvt_pk_bf16_f32 v22, v25, v23
	v_cvt_pk_bf16_f32 v23, v27, v29
	v_cvt_pk_bf16_f32 v24, v31, v33
	v_cvt_pk_bf16_f32 v25, v45, v47
	s_waitcnt lgkmcnt(6)
	v_cvt_pk_bf16_f32 v26, v50, v48
	s_waitcnt lgkmcnt(4)
	v_cvt_pk_bf16_f32 v27, v52, v54
	s_waitcnt lgkmcnt(2)
	v_cvt_pk_bf16_f32 v28, v56, v58
	s_waitcnt lgkmcnt(0)
	v_cvt_pk_bf16_f32 v29, v60, v62
	v_cvt_pk_bf16_f32 v30, v51, v49
	v_cvt_pk_bf16_f32 v31, v53, v55
	v_cvt_pk_bf16_f32 v32, v57, v59
	v_cvt_pk_bf16_f32 v33, v61, v63
	global_store_dwordx4 v[34:35], v[18:21], off
	global_store_dwordx4 v[38:39], v[22:25], off
	global_store_dwordx4 v[40:41], v[26:29], off
	global_store_dwordx4 v[42:43], v[30:33], off
	s_waitcnt lgkmcnt(0)
	s_add_i32 s8, s8, s101
	s_add_i32 s6, s6, s7
	s_cmpk_lt_i32 s8, 0x1000
	s_cbranch_scc1 .LBB0_32
